# attention mid-iteration barrier: next-tile test hoisted above it, on top of the stacked loop-edge edits
# speedup vs baseline: 1.0001x; 1.0001x over previous
; __device__ __forceinline__ void lds_barrier() { asm volatile("s_waitcnt lgkmcnt(0)" ::: "memory"); __builtin_amdgcn_s_barrier(); asm volatile("" ::: "memory"); }
; __device__ __forceinline__ u32x4 gload16_asm(const void* p) { u32x4 r; asm volatile("global_load_dwordx4 %0, %1, off" : "=v"(r) : "v"(p) : "memory"); return r; }
; __device__ __forceinline__ void attn_phase(const Args& a, LAS unsigned char* lds, const bf16* Qn, const bf16* Kn, const bf16* Vt, bf16* O, float* stash, int tid, int lane, int wave) {
;     ...
;                 if (t + 2 < NT) { kreg[hh] = gload16_asm(Kp + (size_t)(t + 2) * 4096); vreg0[hh] = gload16_asm(Vp + 64 * (t + 2)); vreg1[hh] = gload16_asm(Vp + (size_t)64 * SEQ + 64 * (t + 2)); }
;                 if (t <= td) {
;     ...
;                 lds_barrier();
.LBB0_120:
	s_add_i32 s22, s2, 3
	s_cmp_ge_u32 s22, s33
	s_waitcnt lgkmcnt(0)
	s_barrier
	s_cbranch_scc1 .LBB0_126
	global_load_dwordx4 v[128:131], v[192:193], off
	global_load_dwordx4 v[136:139], v[188:189], off
	global_load_dwordx4 v[144:147], v[190:191], off
	s_cmp_ge_i32 s2, s30
	s_cbranch_scc0 .LBB0_127
